# grid barriers whose downstream consumers stay XCD-local until the next flushing barrier (end-of-layer; post-down1 in MLA layers) skip the L2 write-back in physical-XCD mode; on top of v73
# speedup vs baseline: 1.0176x; 1.0014x over previous
; DI void grid_bar(unsigned* ctr, unsigned target) {
;   asm volatile("s_waitcnt vmcnt(0)" ::: "memory");
;   __syncthreads();
;   if (threadIdx.x == 0) {
;     __builtin_amdgcn_fence(__ATOMIC_RELEASE, "agent");
;     asm volatile("s_waitcnt vmcnt(0)" ::: "memory");
;     (void)__hip_atomic_fetch_add(ctr, 1u, __ATOMIC_RELAXED, __HIP_MEMORY_SCOPE_AGENT);
;     while (__hip_atomic_load(ctr, __ATOMIC_RELAXED, __HIP_MEMORY_SCOPE_AGENT) < target) __builtin_amdgcn_s_sleep(1);
;     __builtin_amdgcn_fence(__ATOMIC_ACQUIRE, "agent");
;     asm volatile("s_waitcnt vmcnt(0)" ::: "memory");
;   }
;   __syncthreads();
; }
.LBB0_616:
	s_waitcnt vmcnt(0)
	v_readlane_b32 s0, v254, 12
	s_add_i32 s31, s74, s0
	s_barrier
	s_mov_b64 s[0:1], exec
	v_readlane_b32 s2, v254, 13
	v_readlane_b32 s3, v254, 14
	s_and_b64 s[2:3], s[0:1], s[2:3]
	s_mov_b64 exec, s[2:3]
	s_cbranch_execz .LBB0_622
	s_mov_b64 s[2:3], exec
	v_readlane_b32 s99, v253, 46
	s_and_b32 s99, s99, s12
	s_bitcmp1_b32 s99, 0
	s_cbranch_scc1 .Lgnowb_1
	buffer_wbl2 sc1
.Lgnowb_1:
	s_waitcnt vmcnt(0)
	s_waitcnt vmcnt(0)
	v_mbcnt_lo_u32_b32 v0, s2, 0
	v_mbcnt_hi_u32_b32 v0, s3, v0
	v_cmp_eq_u32_e32 vcc, 0, v0
	s_and_saveexec_b64 s[8:9], vcc
	s_cbranch_execz .LBB0_619
	s_bcnt1_i32_b64 s2, s[2:3]
	v_mov_b32_e32 v0, s2
	global_atomic_add v1, v0, s[14:15]
.LBB0_619:
	s_or_b64 exec, exec, s[8:9]
	global_load_dword v0, v1, s[14:15] sc1
	s_waitcnt vmcnt(0)
	v_cmp_le_u32_e32 vcc, s31, v0
	s_cbranch_vccnz .LBB0_621

; DI void grid_bar(unsigned* ctr, unsigned target) {
;   asm volatile("s_waitcnt vmcnt(0)" ::: "memory");
;   __syncthreads();
;   if (threadIdx.x == 0) {
;     __builtin_amdgcn_fence(__ATOMIC_RELEASE, "agent");
;     asm volatile("s_waitcnt vmcnt(0)" ::: "memory");
;     (void)__hip_atomic_fetch_add(ctr, 1u, __ATOMIC_RELAXED, __HIP_MEMORY_SCOPE_AGENT);
;     while (__hip_atomic_load(ctr, __ATOMIC_RELAXED, __HIP_MEMORY_SCOPE_AGENT) < target) __builtin_amdgcn_s_sleep(1);
;     __builtin_amdgcn_fence(__ATOMIC_ACQUIRE, "agent");
.LBB0_1829:
	s_mov_b64 s[2:3], exec
	v_readlane_b32 s99, v253, 46
	s_cmp_lg_u32 s99, 0
	s_cbranch_scc1 .Lgnowb_0
	buffer_wbl2 sc1
.Lgnowb_0:
	s_waitcnt vmcnt(0)
	s_waitcnt vmcnt(0)
	v_mbcnt_lo_u32_b32 v0, s2, 0
	v_mbcnt_hi_u32_b32 v0, s3, v0
	v_cmp_eq_u32_e32 vcc, 0, v0
	s_and_saveexec_b64 s[4:5], vcc
	s_cbranch_execz .LBB0_1831
	s_bcnt1_i32_b64 s2, s[2:3]
	v_mov_b32_e32 v0, s2
	global_atomic_add v1, v0, s[14:15]
